# E39: weight-conversion unit: the 16 gain scalars requested together right after the weight loads instead of 16 dependent load-wait-use round trips; on E35
# speedup vs baseline: 1.0051x; 1.0051x over previous
.LBB0_535:
	v_cvt_f32_u32_e32 v4, s46
	s_sub_i32 s50, 0, s46
	s_abs_i32 s45, s47
	s_mulk_i32 s18, 0x4100
	v_rcp_iflag_f32_e32 v4, v4
	s_ashr_i32 s44, s47, 31
	s_add_i32 s18, s18, 0
	v_mov_b32_e32 v165, v5
	v_mul_f32_e32 v4, 0x4f7ffffe, v4
	v_cvt_u32_f32_e32 v4, v4
	v_add_u32_e32 v72, s18, v164
	v_add_u32_e32 v73, v72, v194
	v_readfirstlane_b32 s51, v4
	s_mul_i32 s50, s50, s51
	s_mul_hi_u32 s50, s51, s50
	s_add_i32 s51, s51, s50
	s_mul_hi_u32 s50, s45, s51
	s_mul_i32 s51, s50, s46
	s_sub_i32 s45, s45, s51
	s_add_i32 s58, s50, 1
	s_sub_i32 s51, s45, s46
	s_cmp_ge_u32 s45, s46
	s_cselect_b32 s50, s58, s50
	s_cselect_b32 s45, s51, s45
	s_add_i32 s51, s50, 1
	s_cmp_ge_u32 s45, s46
	s_cselect_b32 s45, s51, s50
	s_xor_b32 s45, s45, s44
	s_sub_i32 s44, s45, s44
	s_mul_i32 s45, s44, s46
	s_lshl_b32 s46, s44, 6
	s_sub_i32 s44, s47, s45
	s_lshl_b32 s44, s44, 6
	s_ashr_i32 s45, s44, 31
	s_lshl_b64 s[50:51], s[44:45], 2
	v_or_b32_e32 v70, s46, v154
	s_add_u32 s48, s48, s50
	s_addc_u32 s49, s49, s51
	v_ashrrev_i32_e32 v71, 31, v70
	v_lshl_add_u64 v[6:7], s[48:49], 0, v[164:165]
	v_mul_lo_u32 v4, s4, v71
	v_mul_lo_u32 v10, s5, v70
	v_mad_u64_u32 v[8:9], s[48:49], s4, v70, 0
	v_add3_u32 v9, v9, v4, v10
	v_or_b32_e32 v10, 4, v70
	v_mul_lo_u32 v12, s5, v10
	v_mad_u64_u32 v[10:11], s[48:49], s4, v10, 0
	v_lshl_add_u64 v[8:9], v[8:9], 2, v[6:7]
	v_add3_u32 v11, v11, v4, v12
	v_lshl_add_u64 v[10:11], v[10:11], 2, v[6:7]
	global_load_dwordx4 v[66:69], v[8:9], off nt
	global_load_dwordx4 v[62:65], v[10:11], off nt
	v_or_b32_e32 v8, 8, v70
	v_mul_lo_u32 v10, s5, v8
	v_mad_u64_u32 v[8:9], s[48:49], s4, v8, 0
	v_add3_u32 v9, v9, v4, v10
	v_or_b32_e32 v10, 12, v70
	v_mul_lo_u32 v12, s5, v10
	v_mad_u64_u32 v[10:11], s[48:49], s4, v10, 0
	v_lshl_add_u64 v[8:9], v[8:9], 2, v[6:7]
	v_add3_u32 v11, v11, v4, v12
	v_lshl_add_u64 v[10:11], v[10:11], 2, v[6:7]
	global_load_dwordx4 v[58:61], v[8:9], off nt
	global_load_dwordx4 v[54:57], v[10:11], off nt
	v_or_b32_e32 v8, 16, v70
	v_mul_lo_u32 v10, s5, v8
	v_mad_u64_u32 v[8:9], s[48:49], s4, v8, 0
	v_add3_u32 v9, v9, v4, v10
	v_or_b32_e32 v10, 20, v70
	v_mul_lo_u32 v12, s5, v10
	v_mad_u64_u32 v[10:11], s[48:49], s4, v10, 0
	v_lshl_add_u64 v[8:9], v[8:9], 2, v[6:7]
	v_add3_u32 v11, v11, v4, v12
	v_lshl_add_u64 v[10:11], v[10:11], 2, v[6:7]
	global_load_dwordx4 v[50:53], v[8:9], off nt
	global_load_dwordx4 v[46:49], v[10:11], off nt
	v_or_b32_e32 v8, 24, v70
	v_mul_lo_u32 v10, s5, v8
	v_mad_u64_u32 v[8:9], s[48:49], s4, v8, 0
	v_add3_u32 v9, v9, v4, v10
	v_or_b32_e32 v10, 28, v70
	v_mul_lo_u32 v12, s5, v10
	v_mad_u64_u32 v[10:11], s[48:49], s4, v10, 0
	v_lshl_add_u64 v[8:9], v[8:9], 2, v[6:7]
	v_add3_u32 v11, v11, v4, v12
	v_lshl_add_u64 v[10:11], v[10:11], 2, v[6:7]
	global_load_dwordx4 v[42:45], v[8:9], off nt
	global_load_dwordx4 v[38:41], v[10:11], off nt
	v_or_b32_e32 v8, 32, v70
	v_mul_lo_u32 v10, s5, v8
	v_mad_u64_u32 v[8:9], s[48:49], s4, v8, 0
	v_add3_u32 v9, v9, v4, v10
	v_or_b32_e32 v10, 36, v70
	v_mul_lo_u32 v12, s5, v10
	v_mad_u64_u32 v[10:11], s[48:49], s4, v10, 0
	v_lshl_add_u64 v[8:9], v[8:9], 2, v[6:7]
	v_add3_u32 v11, v11, v4, v12
	v_lshl_add_u64 v[10:11], v[10:11], 2, v[6:7]
	global_load_dwordx4 v[34:37], v[8:9], off nt
	global_load_dwordx4 v[30:33], v[10:11], off nt
	v_or_b32_e32 v8, 40, v70
	v_mul_lo_u32 v10, s5, v8
	v_mad_u64_u32 v[8:9], s[48:49], s4, v8, 0
	v_add3_u32 v9, v9, v4, v10
	v_or_b32_e32 v10, 44, v70
	v_mul_lo_u32 v12, s5, v10
	v_mad_u64_u32 v[10:11], s[48:49], s4, v10, 0
	v_lshl_add_u64 v[8:9], v[8:9], 2, v[6:7]
	v_add3_u32 v11, v11, v4, v12
	v_lshl_add_u64 v[10:11], v[10:11], 2, v[6:7]
	global_load_dwordx4 v[26:29], v[8:9], off nt
	global_load_dwordx4 v[22:25], v[10:11], off nt
	v_or_b32_e32 v8, 48, v70
	v_mul_lo_u32 v10, s5, v8
	v_mad_u64_u32 v[8:9], s[48:49], s4, v8, 0
	v_add3_u32 v9, v9, v4, v10
	v_or_b32_e32 v10, 52, v70
	v_mul_lo_u32 v12, s5, v10
	v_mad_u64_u32 v[10:11], s[48:49], s4, v10, 0
	v_lshl_add_u64 v[8:9], v[8:9], 2, v[6:7]
	v_add3_u32 v11, v11, v4, v12
	v_lshl_add_u64 v[10:11], v[10:11], 2, v[6:7]
	global_load_dwordx4 v[18:21], v[8:9], off nt
	global_load_dwordx4 v[14:17], v[10:11], off nt
	v_or_b32_e32 v8, 56, v70
	v_mul_lo_u32 v10, s5, v8
	v_mad_u64_u32 v[8:9], s[48:49], s4, v8, 0
	v_add3_u32 v9, v9, v4, v10
	v_or_b32_e32 v10, 60, v70
	v_mul_lo_u32 v12, s5, v10
	v_mad_u64_u32 v[10:11], s[4:5], s4, v10, 0
	v_add3_u32 v11, v11, v4, v12
	v_lshl_add_u64 v[8:9], v[8:9], 2, v[6:7]
	v_lshl_add_u64 v[6:7], v[10:11], 2, v[6:7]
	global_load_dwordx4 v[10:13], v[8:9], off nt
	s_nop 0
	global_load_dwordx4 v[6:9], v[6:7], off nt
	s_cmp_lg_u64 s[42:43], 0
	s_cselect_b64 s[48:49], -1, 0
	s_cmp_eq_u64 s[42:43], 0
	s_cbranch_scc1 .LBB0_558
	v_lshl_add_u64 v[70:71], v[70:71], 2, s[42:43]
	global_load_dword v74, v[70:71], off
	s_ashr_i32 s47, s46, 31
	v_lshl_add_u64 v[90:91], s[46:47], 0, v[154:155]
	v_lshl_add_u64 v[90:91], v[90:91], 2, s[42:43]
	global_load_dword v75, v[90:91], off offset:16
	global_load_dword v76, v[90:91], off offset:32
	global_load_dword v77, v[90:91], off offset:48
	global_load_dword v78, v[90:91], off offset:64
	global_load_dword v79, v[90:91], off offset:80
	global_load_dword v80, v[90:91], off offset:96
	global_load_dword v81, v[90:91], off offset:112
	global_load_dword v82, v[90:91], off offset:128
	global_load_dword v83, v[90:91], off offset:144
	global_load_dword v84, v[90:91], off offset:160
	global_load_dword v85, v[90:91], off offset:176
	global_load_dword v86, v[90:91], off offset:192
	global_load_dword v87, v[90:91], off offset:208
	global_load_dword v88, v[90:91], off offset:224
	global_load_dword v89, v[90:91], off offset:240
	s_waitcnt vmcnt(0)
	v_mov_b32_e32 v4, v74
	v_pk_mul_f32 v[70:71], v[66:67], v[4:5] op_sel_hi:[1,0]
	ds_write2_b32 v73, v70, v71 offset1:1
	v_pk_mul_f32 v[70:71], v[68:69], v[4:5] op_sel_hi:[1,0]
	ds_write2_b32 v73, v70, v71 offset0:2 offset1:3
	v_lshl_add_u64 v[70:71], s[46:47], 0, v[154:155]
	v_lshl_add_u64 v[70:71], v[70:71], 2, s[42:43]
	v_mov_b32_e32 v4, v75
	s_cbranch_execnz .LBB0_538

.LBB0_538:
	s_waitcnt vmcnt(15)
	v_add_u32_e32 v66, v72, v195
	s_waitcnt vmcnt(0)
	v_pk_mul_f32 v[62:63], v[62:63], v[4:5] op_sel_hi:[1,0]
	ds_write2_b32 v66, v62, v63 offset1:1
	v_pk_mul_f32 v[62:63], v[64:65], v[4:5] op_sel_hi:[1,0]
	v_cndmask_b32_e64 v4, 0, 1, s[48:49]
	ds_write2_b32 v66, v62, v63 offset0:2 offset1:3
	v_cmp_ne_u32_e64 s[4:5], 1, v4
	s_andn2_b64 vcc, exec, s[48:49]
	v_add_u32_e32 v62, v72, v196
	s_cbranch_vccnz .LBB0_559
	s_ashr_i32 s47, s46, 31
	v_lshl_add_u64 v[64:65], s[46:47], 0, v[154:155]
	v_lshl_add_u64 v[64:65], v[64:65], 2, s[42:43]
	v_mov_b32_e32 v4, v76
	s_waitcnt vmcnt(0)
	v_pk_mul_f32 v[66:67], v[58:59], v[4:5] op_sel_hi:[1,0]
	ds_write2_b32 v62, v66, v67 offset1:1
	v_pk_mul_f32 v[66:67], v[60:61], v[4:5] op_sel_hi:[1,0]
	v_mov_b32_e32 v4, v77
	ds_write2_b32 v62, v66, v67 offset0:2 offset1:3
	s_cbranch_execnz .LBB0_541

.LBB0_541:
	v_add_u32_e32 v58, v72, v197
	s_waitcnt vmcnt(0)
	v_pk_mul_f32 v[54:55], v[54:55], v[4:5] op_sel_hi:[1,0]
	ds_write2_b32 v58, v54, v55 offset1:1
	v_pk_mul_f32 v[54:55], v[56:57], v[4:5] op_sel_hi:[1,0]
	ds_write2_b32 v58, v54, v55 offset0:2 offset1:3
	s_and_b64 vcc, exec, s[4:5]
	v_add_u32_e32 v54, 0x410, v58
	v_add_u32_e32 v55, 0x418, v58
	s_cbranch_vccnz .LBB0_560
	s_ashr_i32 s47, s46, 31
	v_lshl_add_u64 v[56:57], s[46:47], 0, v[154:155]
	v_lshl_add_u64 v[56:57], v[56:57], 2, s[42:43]
	v_mov_b32_e32 v4, v78
	s_waitcnt vmcnt(0)
	v_pk_mul_f32 v[60:61], v[50:51], v[4:5] op_sel_hi:[1,0]
	ds_write2_b32 v54, v60, v61 offset1:1
	v_pk_mul_f32 v[60:61], v[52:53], v[4:5] op_sel_hi:[1,0]
	v_mov_b32_e32 v4, v79
	ds_write2_b32 v55, v60, v61 offset1:1
	s_cbranch_execnz .LBB0_544

.LBB0_544:
	s_waitcnt vmcnt(0)
	v_pk_mul_f32 v[46:47], v[46:47], v[4:5] op_sel_hi:[1,0]
	v_add_u32_e32 v50, 0x820, v58
	ds_write2_b32 v50, v46, v47 offset1:1
	v_pk_mul_f32 v[46:47], v[48:49], v[4:5] op_sel_hi:[1,0]
	v_add_u32_e32 v4, 0x828, v58
	ds_write2_b32 v4, v46, v47 offset1:1
	s_and_b64 vcc, exec, s[4:5]
	v_add_u32_e32 v46, 0xc30, v58
	v_add_u32_e32 v47, 0xc38, v58
	s_cbranch_vccnz .LBB0_561
	s_ashr_i32 s47, s46, 31
	v_lshl_add_u64 v[48:49], s[46:47], 0, v[154:155]
	v_lshl_add_u64 v[48:49], v[48:49], 2, s[42:43]
	v_mov_b32_e32 v4, v80
	s_waitcnt vmcnt(0)
	v_pk_mul_f32 v[50:51], v[42:43], v[4:5] op_sel_hi:[1,0]
	ds_write2_b32 v46, v50, v51 offset1:1
	v_pk_mul_f32 v[50:51], v[44:45], v[4:5] op_sel_hi:[1,0]
	v_mov_b32_e32 v4, v81
	ds_write2_b32 v47, v50, v51 offset1:1
	s_cbranch_execnz .LBB0_547

.LBB0_547:
	s_waitcnt vmcnt(0)
	v_pk_mul_f32 v[38:39], v[38:39], v[4:5] op_sel_hi:[1,0]
	v_add_u32_e32 v42, 0x1040, v58
	ds_write2_b32 v42, v38, v39 offset1:1
	v_pk_mul_f32 v[38:39], v[40:41], v[4:5] op_sel_hi:[1,0]
	v_add_u32_e32 v4, 0x1048, v58
	ds_write2_b32 v4, v38, v39 offset1:1
	s_and_b64 vcc, exec, s[4:5]
	v_add_u32_e32 v38, 0x1450, v58
	v_add_u32_e32 v39, 0x1458, v58
	s_cbranch_vccnz .LBB0_562
	s_ashr_i32 s47, s46, 31
	v_lshl_add_u64 v[40:41], s[46:47], 0, v[154:155]
	v_lshl_add_u64 v[40:41], v[40:41], 2, s[42:43]
	v_mov_b32_e32 v4, v82
	s_waitcnt vmcnt(0)
	v_pk_mul_f32 v[42:43], v[34:35], v[4:5] op_sel_hi:[1,0]
	ds_write2_b32 v38, v42, v43 offset1:1
	v_pk_mul_f32 v[42:43], v[36:37], v[4:5] op_sel_hi:[1,0]
	v_mov_b32_e32 v4, v83
	ds_write2_b32 v39, v42, v43 offset1:1
	s_cbranch_execnz .LBB0_550

.LBB0_550:
	s_waitcnt vmcnt(0)
	v_pk_mul_f32 v[30:31], v[30:31], v[4:5] op_sel_hi:[1,0]
	v_add_u32_e32 v34, 0x1860, v58
	ds_write2_b32 v34, v30, v31 offset1:1
	v_pk_mul_f32 v[30:31], v[32:33], v[4:5] op_sel_hi:[1,0]
	v_add_u32_e32 v4, 0x1868, v58
	ds_write2_b32 v4, v30, v31 offset1:1
	s_and_b64 vcc, exec, s[4:5]
	v_add_u32_e32 v30, 0x1c70, v58
	v_add_u32_e32 v31, 0x1c78, v58
	s_cbranch_vccnz .LBB0_563
	s_ashr_i32 s47, s46, 31
	v_lshl_add_u64 v[32:33], s[46:47], 0, v[154:155]
	v_lshl_add_u64 v[32:33], v[32:33], 2, s[42:43]
	v_mov_b32_e32 v4, v84
	s_waitcnt vmcnt(0)
	v_pk_mul_f32 v[34:35], v[26:27], v[4:5] op_sel_hi:[1,0]
	ds_write2_b32 v30, v34, v35 offset1:1
	v_pk_mul_f32 v[34:35], v[28:29], v[4:5] op_sel_hi:[1,0]
	v_mov_b32_e32 v4, v85
	ds_write2_b32 v31, v34, v35 offset1:1
	s_cbranch_execnz .LBB0_553

.LBB0_553:
	s_waitcnt vmcnt(0)
	v_pk_mul_f32 v[22:23], v[22:23], v[4:5] op_sel_hi:[1,0]
	v_add_u32_e32 v26, 0x2080, v58
	ds_write2_b32 v26, v22, v23 offset1:1
	v_pk_mul_f32 v[22:23], v[24:25], v[4:5] op_sel_hi:[1,0]
	v_add_u32_e32 v4, 0x2088, v58
	ds_write2_b32 v4, v22, v23 offset1:1
	s_and_b64 vcc, exec, s[4:5]
	v_add_u32_e32 v22, 0x2490, v58
	v_add_u32_e32 v23, 0x2498, v58
	s_cbranch_vccnz .LBB0_564
	s_ashr_i32 s47, s46, 31
	v_lshl_add_u64 v[24:25], s[46:47], 0, v[154:155]
	v_lshl_add_u64 v[24:25], v[24:25], 2, s[42:43]
	v_mov_b32_e32 v4, v86
	s_waitcnt vmcnt(0)
	v_pk_mul_f32 v[26:27], v[18:19], v[4:5] op_sel_hi:[1,0]
	ds_write2_b32 v22, v26, v27 offset1:1
	v_pk_mul_f32 v[26:27], v[20:21], v[4:5] op_sel_hi:[1,0]
	v_mov_b32_e32 v4, v87
	ds_write2_b32 v23, v26, v27 offset1:1
	s_cbranch_execnz .LBB0_556

.LBB0_556:
	s_waitcnt vmcnt(0)
	v_pk_mul_f32 v[14:15], v[14:15], v[4:5] op_sel_hi:[1,0]
	v_add_u32_e32 v18, 0x28a0, v58
	ds_write2_b32 v18, v14, v15 offset1:1
	v_pk_mul_f32 v[14:15], v[16:17], v[4:5] op_sel_hi:[1,0]
	v_add_u32_e32 v4, 0x28a8, v58
	ds_write2_b32 v4, v14, v15 offset1:1
	s_and_b64 vcc, exec, s[4:5]
	v_add_u32_e32 v14, 0x2cb0, v58
	v_add_u32_e32 v15, 0x2cb8, v58
	s_cbranch_vccnz .LBB0_565
	s_ashr_i32 s47, s46, 31
	v_lshl_add_u64 v[16:17], s[46:47], 0, v[154:155]
	v_lshl_add_u64 v[16:17], v[16:17], 2, s[42:43]
	v_mov_b32_e32 v18, v88
	v_mov_b32_e32 v4, v89
	s_waitcnt vmcnt(1)
	v_pk_mul_f32 v[16:17], v[10:11], v[18:19] op_sel_hi:[1,0]
	v_pk_mul_f32 v[18:19], v[12:13], v[18:19] op_sel_hi:[1,0]
	ds_write2_b32 v14, v16, v17 offset1:1
	ds_write2_b32 v15, v18, v19 offset1:1
	s_cbranch_execnz .LBB0_313
	s_branch .LBB0_312
